# dense attention MFMA segment: fragment reads three ahead (issued after the second MFMA of fragment i into its own buffer), three pre-reads (v61 + p3)
# baseline (speedup 1.0000x reference)
.LBB0_1012:
	s_ashr_i32 s39, s0, 7
	s_lshl_b32 s4, s0, 9
	s_bfe_u32 s1, s0, 0x40003
	s_and_b32 s40, s4, 0xe00
	s_lshl_b32 s4, s39, 4
	s_or_b32 s4, s4, s1
	s_add_i32 s40, s40, s38
	s_ashr_i32 s5, s4, 31
	s_lshr_b32 s6, s0, 3
	s_lshl_b64 s[4:5], s[4:5], 12
	s_ashr_i32 s7, s40, 31
	s_add_u32 s4, s4, s40
	s_addc_u32 s5, s5, s7
	v_mov_b32_e32 v1, s5
	v_or_b32_e32 v0, s4, v202
	s_bfe_u32 s4, s6, 0x20002
	s_lshl_b32 s5, s39, 2
	s_or_b32 s4, s4, s5
	v_lshlrev_b64 v[0:1], 7, v[0:1]
	s_ashr_i32 s5, s4, 31
	v_lshl_add_u64 v[2:3], v[204:205], 0, v[0:1]
	v_or_b32_e32 v0, 0x1000, v0
	s_lshl_b64 s[4:5], s[4:5], 19
	v_lshl_add_u64 v[0:1], v[204:205], 0, v[0:1]
	v_lshl_add_u64 v[212:213], v[208:209], 0, s[4:5]
	global_load_dwordx4 v[130:133], v[2:3], off
	global_load_dwordx4 v[134:137], v[2:3], off offset:32
	global_load_dwordx4 v[138:141], v[2:3], off offset:64
	global_load_dwordx4 v[142:145], v[2:3], off offset:96
	global_load_dwordx4 v[146:149], v[0:1], off
	global_load_dwordx4 v[150:153], v[0:1], off offset:32
	global_load_dwordx4 v[154:157], v[0:1], off offset:64
	global_load_dwordx4 v[158:161], v[0:1], off offset:96
	v_lshl_add_u64 v[214:215], v[210:211], 0, s[4:5]
	global_load_dwordx4 v[0:3], v[212:213], off
	global_load_dwordx4 v[4:7], v[214:215], off
	s_mov_b64 s[6:7], 0x2000
	v_lshl_add_u64 v[182:183], v[212:213], 0, s[6:7]
	global_load_dwordx4 v[182:185], v[182:183], off
	global_load_dwordx4 v[178:181], v[214:215], off offset:128
	v_mov_b32_e32 v82, 0xf149f2ca
	s_mov_b32 s4, 0
	s_movk_i32 s42, 0x6c00
	s_movk_i32 s41, 0x4800
	s_mov_b32 s5, 0x9000
	v_mov_b32_e32 v162, 0
	v_mov_b32_e32 v163, 0
	v_mov_b32_e32 v164, 0
	v_mov_b32_e32 v165, 0
	v_mov_b32_e32 v174, 0
	v_mov_b32_e32 v175, 0
	v_mov_b32_e32 v176, 0
	v_mov_b32_e32 v177, 0
	v_mov_b32_e32 v166, 0
	v_mov_b32_e32 v167, 0
	v_mov_b32_e32 v168, 0
	v_mov_b32_e32 v169, 0
	v_mov_b32_e32 v170, 0
	v_mov_b32_e32 v171, 0
	v_mov_b32_e32 v172, 0
	v_mov_b32_e32 v173, 0
	v_mov_b32_e32 v83, v82
	v_mov_b32_e32 v84, v82
	v_mov_b32_e32 v85, v82
	v_mov_b32_e32 v86, v82
	v_mov_b32_e32 v87, v82
	v_mov_b32_e32 v88, v82
	v_mov_b32_e32 v89, v82
	v_mov_b32_e32 v90, v82
	v_mov_b32_e32 v91, v82
	v_mov_b32_e32 v92, v82
	v_mov_b32_e32 v93, v82
	v_mov_b32_e32 v94, v82
	v_mov_b32_e32 v95, v82
	v_mov_b32_e32 v96, v82
	v_mov_b32_e32 v97, v82
	v_mov_b32_e32 v66, v82
	v_mov_b32_e32 v67, v82
	v_mov_b32_e32 v68, v82
	v_mov_b32_e32 v69, v82
	v_mov_b32_e32 v70, v82
	v_mov_b32_e32 v71, v82
	v_mov_b32_e32 v72, v82
	v_mov_b32_e32 v73, v82
	v_mov_b32_e32 v74, v82
	v_mov_b32_e32 v75, v82
	v_mov_b32_e32 v76, v82
	v_mov_b32_e32 v77, v82
	v_mov_b32_e32 v78, v82
	v_mov_b32_e32 v79, v82
	v_mov_b32_e32 v80, v82
	v_mov_b32_e32 v81, v82
	s_waitcnt vmcnt(3)
	ds_write_b128 v203, v[0:3]
	s_waitcnt vmcnt(2)
	ds_write_b128 v203, v[4:7] offset:18432
	v_mov_b32_e32 v0, 0
	v_mov_b32_e32 v1, v0
	v_mov_b32_e32 v2, v0
	v_mov_b32_e32 v3, v0
	v_mov_b32_e32 v4, v0
	v_mov_b32_e32 v5, v0
	v_mov_b32_e32 v6, v0
	v_mov_b32_e32 v7, v0
	v_mov_b32_e32 v8, v0
	v_mov_b32_e32 v9, v0
	v_mov_b32_e32 v10, v0
	v_mov_b32_e32 v11, v0
	v_mov_b32_e32 v12, v0
	v_mov_b32_e32 v13, v0
	v_mov_b32_e32 v14, v0
	v_mov_b32_e32 v15, v0
	v_mov_b32_e32 v16, v0
	v_mov_b32_e32 v17, v0
	v_mov_b32_e32 v18, v0
	v_mov_b32_e32 v19, v0
	v_mov_b32_e32 v20, v0
	v_mov_b32_e32 v21, v0
	v_mov_b32_e32 v22, v0
	v_mov_b32_e32 v23, v0
	v_mov_b32_e32 v24, v0
	v_mov_b32_e32 v25, v0
	v_mov_b32_e32 v26, v0
	v_mov_b32_e32 v27, v0
	v_mov_b32_e32 v28, v0
	v_mov_b32_e32 v29, v0
	v_mov_b32_e32 v30, v0
	v_mov_b32_e32 v31, v0
	v_mov_b32_e32 v34, v0
	v_mov_b32_e32 v35, v0
	v_mov_b32_e32 v36, v0
	v_mov_b32_e32 v37, v0
	v_mov_b32_e32 v38, v0
	v_mov_b32_e32 v39, v0
	v_mov_b32_e32 v40, v0
	v_mov_b32_e32 v41, v0
	v_mov_b32_e32 v42, v0
	v_mov_b32_e32 v43, v0
	v_mov_b32_e32 v44, v0
	v_mov_b32_e32 v45, v0
	v_mov_b32_e32 v46, v0
	v_mov_b32_e32 v47, v0
	v_mov_b32_e32 v48, v0
	v_mov_b32_e32 v49, v0
	v_mov_b32_e32 v50, v0
	v_mov_b32_e32 v51, v0
	v_mov_b32_e32 v52, v0
	v_mov_b32_e32 v53, v0
	v_mov_b32_e32 v54, v0
	v_mov_b32_e32 v55, v0
	v_mov_b32_e32 v56, v0
	v_mov_b32_e32 v57, v0
	v_mov_b32_e32 v58, v0
	v_mov_b32_e32 v59, v0
	v_mov_b32_e32 v60, v0
	v_mov_b32_e32 v61, v0
	v_mov_b32_e32 v62, v0
	v_mov_b32_e32 v63, v0
	v_mov_b32_e32 v64, v0
	v_mov_b32_e32 v65, v0
	v_mov_b32_e32 v216, v0
	v_mov_b32_e32 v217, v0
	s_waitcnt lgkmcnt(0)
	s_barrier
	v_mov_b32_e32 v234, v245
	v_add_u32_e32 v235, s5, v32
	s_cmpk_lt_u32 s38, 0x100
	s_cselect_b32 s101, 0, 1
	v_mov_b32_e32 v186, 0
	v_mov_b32_e32 v187, 0
	v_mov_b32_e32 v188, 0
	v_mov_b32_e32 v189, 0
	v_mov_b32_e32 v190, 0
	v_mov_b32_e32 v191, 0
	v_mov_b32_e32 v192, 0
	v_mov_b32_e32 v193, 0
	v_mov_b32_e32 v218, 0
	v_mov_b32_e32 v219, 0
	v_mov_b32_e32 v220, 0
	v_mov_b32_e32 v221, 0
	v_mov_b32_e32 v222, 0
	v_mov_b32_e32 v223, 0
	v_mov_b32_e32 v224, 0
	v_mov_b32_e32 v225, 0
	ds_read_b128 v[226:229], v235
	ds_read_b128 v[230:233], v235 offset:4608
	ds_read_b128 v[246:249], v235 offset:32
.LBB0_1013:
	s_waitcnt lgkmcnt(2)
	v_mfma_f32_32x32x16_bf16 v[50:65], v[226:229], v[170:173], v[50:65]
	v_mfma_f32_32x32x16_bf16 v[16:31], v[226:229], v[174:177], v[16:31]
	ds_read_b128 v[226:229], v235 offset:4640
	s_add_i32 s44, s4, 1
	s_and_b32 s43, s44, 1
	s_mul_i32 s43, s43, 0x2400
	s_waitcnt lgkmcnt(2)
	v_mfma_f32_32x32x16_bf16 v[34:49], v[230:233], v[170:173], v[34:49]
	v_add_u32_e32 v198, s43, v203
	v_add_u32_e32 v199, s42, v203
	v_mfma_f32_32x32x16_bf16 v[0:15], v[230:233], v[174:177], v[0:15]
	ds_read_b128 v[230:233], v235 offset:64
	s_add_i32 s16, s4, 2
	s_min_u32 s16, s16, 63
	s_waitcnt lgkmcnt(2)
	v_mfma_f32_32x32x16_bf16 v[50:65], v[246:249], v[166:169], v[50:65]
	v_mfma_f32_32x32x16_bf16 v[16:31], v[246:249], v[162:165], v[16:31]
	ds_read_b128 v[246:249], v235 offset:4672
	s_waitcnt lgkmcnt(2)
	v_mfma_f32_32x32x16_bf16 v[34:49], v[226:229], v[166:169], v[34:49]
	v_mfma_f32_32x32x16_bf16 v[0:15], v[226:229], v[162:165], v[0:15]
	ds_read_b128 v[226:229], v235 offset:96
	s_waitcnt lgkmcnt(2)
	v_mfma_f32_32x32x16_bf16 v[50:65], v[230:233], v[186:189], v[50:65]
	v_mfma_f32_32x32x16_bf16 v[16:31], v[230:233], v[218:221], v[16:31]
	ds_read_b128 v[230:233], v235 offset:4704
	s_waitcnt lgkmcnt(2)
	v_mfma_f32_32x32x16_bf16 v[34:49], v[246:249], v[186:189], v[34:49]
	v_mfma_f32_32x32x16_bf16 v[0:15], v[246:249], v[218:221], v[0:15]
	ds_read_b128 v[246:249], v234
	s_waitcnt lgkmcnt(2)
	v_mfma_f32_32x32x16_bf16 v[50:65], v[226:229], v[190:193], v[50:65]
	v_mfma_f32_32x32x16_bf16 v[16:31], v[226:229], v[222:225], v[16:31]
	ds_read_b128 v[226:229], v234 offset:32
	s_waitcnt lgkmcnt(2)
	v_mfma_f32_32x32x16_bf16 v[34:49], v[230:233], v[190:193], v[34:49]
	v_mfma_f32_32x32x16_bf16 v[0:15], v[230:233], v[222:225], v[0:15]
	ds_read_b128 v[230:233], v234 offset:64
	s_waitcnt lgkmcnt(2)
	v_mfma_f32_32x32x16_bf16 v[114:129], v[246:249], v[130:133], 0
	v_mfma_f32_32x32x16_bf16 v[98:113], v[246:249], v[146:149], 0
	ds_read_b128 v[246:249], v234 offset:96
	s_waitcnt lgkmcnt(2)
	v_mfma_f32_32x32x16_bf16 v[114:129], v[226:229], v[134:137], v[114:129]
	s_waitcnt vmcnt(0)
	ds_write_b128 v199, v[178:181]
	v_mfma_f32_32x32x16_bf16 v[98:113], v[226:229], v[150:153], v[98:113]
	ds_read_b128 v[226:229], v234 offset:4608
	s_waitcnt lgkmcnt(3)
	v_mfma_f32_32x32x16_bf16 v[114:129], v[230:233], v[138:141], v[114:129]
	ds_write_b128 v198, v[182:185]
	v_mfma_f32_32x32x16_bf16 v[98:113], v[230:233], v[154:157], v[98:113]
	ds_read_b128 v[230:233], v234 offset:4640
	s_waitcnt lgkmcnt(4)
	v_mfma_f32_32x32x16_bf16 v[114:129], v[246:249], v[142:145], v[114:129]
	s_lshl_b64 s[6:7], s[16:17], 13
	v_lshl_add_u64 v[182:183], v[212:213], 0, s[6:7]
	v_mfma_f32_32x32x16_bf16 v[98:113], v[246:249], v[158:161], v[98:113]
	ds_read_b128 v[246:249], v234 offset:4672
	global_load_dwordx4 v[182:185], v[182:183], off
	s_lshl_b64 s[6:7], s[16:17], 7
	s_waitcnt lgkmcnt(3)
	v_mfma_f32_32x32x16_bf16 v[82:97], v[226:229], v[130:133], 0
	v_lshl_add_u64 v[178:179], v[214:215], 0, s[6:7]
	v_mfma_f32_32x32x16_bf16 v[66:81], v[226:229], v[146:149], 0
	ds_read_b128 v[226:229], v234 offset:4704
	global_load_dwordx4 v[178:181], v[178:179], off
	s_waitcnt lgkmcnt(2)
	v_mfma_f32_32x32x16_bf16 v[82:97], v[230:233], v[134:137], v[82:97]
	v_mfma_f32_32x32x16_bf16 v[66:81], v[230:233], v[150:153], v[66:81]
	s_waitcnt lgkmcnt(1)
	v_mfma_f32_32x32x16_bf16 v[82:97], v[246:249], v[138:141], v[82:97]
	v_mfma_f32_32x32x16_bf16 v[66:81], v[246:249], v[154:157], v[66:81]
	s_waitcnt lgkmcnt(0)
	v_mfma_f32_32x32x16_bf16 v[82:97], v[226:229], v[142:145], v[82:97]
	v_mfma_f32_32x32x16_bf16 v[66:81], v[226:229], v[158:161], v[66:81]
	s_cmp_eq_u32 s101, 1
	s_cbranch_scc0 .Lpp_nb_l1
	s_barrier
.Lpp_nb_l1:
	v_exp_f32_e32 v114, v114
	v_exp_f32_e32 v115, v115
	v_exp_f32_e32 v116, v116
	v_exp_f32_e32 v117, v117
	v_exp_f32_e32 v118, v118
	v_exp_f32_e32 v119, v119
	v_exp_f32_e32 v120, v120
	v_exp_f32_e32 v121, v121
	v_cvt_pk_bf16_f32 v170, v114, v115
	v_add_f32_e32 v114, v114, v115
	v_exp_f32_e32 v122, v122
	v_exp_f32_e32 v123, v123
	v_cvt_pk_bf16_f32 v171, v116, v117
	v_add_f32_e32 v116, v116, v117
	v_add_f32_e32 v217, v217, v114
	v_exp_f32_e32 v124, v124
	v_exp_f32_e32 v125, v125
	v_cvt_pk_bf16_f32 v172, v118, v119
	v_add_f32_e32 v118, v118, v119
	v_add_f32_e32 v217, v217, v116
	v_exp_f32_e32 v126, v126
	v_exp_f32_e32 v127, v127
	v_cvt_pk_bf16_f32 v173, v120, v121
	v_add_f32_e32 v120, v120, v121
	v_add_f32_e32 v217, v217, v118
	v_exp_f32_e32 v128, v128
	v_exp_f32_e32 v129, v129
	v_cvt_pk_bf16_f32 v166, v122, v123
	v_add_f32_e32 v122, v122, v123
	v_add_f32_e32 v217, v217, v120
	v_exp_f32_e32 v98, v98
	v_exp_f32_e32 v99, v99
	v_cvt_pk_bf16_f32 v167, v124, v125
	v_add_f32_e32 v124, v124, v125
	v_add_f32_e32 v217, v217, v122
	v_exp_f32_e32 v100, v100
	v_exp_f32_e32 v101, v101
	v_cvt_pk_bf16_f32 v168, v126, v127
	v_add_f32_e32 v126, v126, v127
	v_add_f32_e32 v217, v217, v124
	v_exp_f32_e32 v102, v102
	v_exp_f32_e32 v103, v103
	v_cvt_pk_bf16_f32 v169, v128, v129
	v_add_f32_e32 v128, v128, v129
	v_add_f32_e32 v217, v217, v126
	v_exp_f32_e32 v104, v104
	v_exp_f32_e32 v105, v105
	v_cvt_pk_bf16_f32 v174, v98, v99
	v_add_f32_e32 v98, v98, v99
	v_add_f32_e32 v217, v217, v128
	v_exp_f32_e32 v106, v106
	v_exp_f32_e32 v107, v107
	v_cvt_pk_bf16_f32 v175, v100, v101
	v_add_f32_e32 v100, v100, v101
	v_add_f32_e32 v216, v216, v98
	v_exp_f32_e32 v108, v108
	v_exp_f32_e32 v109, v109
	v_cvt_pk_bf16_f32 v176, v102, v103
	v_add_f32_e32 v102, v102, v103
	v_add_f32_e32 v216, v216, v100
	v_exp_f32_e32 v110, v110
	v_exp_f32_e32 v111, v111
	v_cvt_pk_bf16_f32 v177, v104, v105
	v_add_f32_e32 v104, v104, v105
	v_add_f32_e32 v216, v216, v102
	v_exp_f32_e32 v112, v112
	v_exp_f32_e32 v113, v113
	v_cvt_pk_bf16_f32 v162, v106, v107
	v_add_f32_e32 v106, v106, v107
	v_add_f32_e32 v216, v216, v104
	v_cvt_pk_bf16_f32 v163, v108, v109
	v_add_f32_e32 v108, v108, v109
	v_add_f32_e32 v216, v216, v106
	v_cvt_pk_bf16_f32 v164, v110, v111
	v_add_f32_e32 v110, v110, v111
	v_add_f32_e32 v216, v216, v108
	v_cvt_pk_bf16_f32 v165, v112, v113
	v_add_f32_e32 v112, v112, v113
	v_add_f32_e32 v216, v216, v110
	v_add_f32_e32 v216, v216, v112
	v_exp_f32_e32 v82, v82
	v_exp_f32_e32 v83, v83
	v_exp_f32_e32 v84, v84
	v_exp_f32_e32 v85, v85
	v_exp_f32_e32 v86, v86
	v_exp_f32_e32 v87, v87
	v_exp_f32_e32 v88, v88
	v_exp_f32_e32 v89, v89
	v_cvt_pk_bf16_f32 v186, v82, v83
	v_add_f32_e32 v82, v82, v83
	v_exp_f32_e32 v90, v90
	v_exp_f32_e32 v91, v91
	v_cvt_pk_bf16_f32 v187, v84, v85
	v_add_f32_e32 v84, v84, v85
	v_add_f32_e32 v217, v217, v82
	v_exp_f32_e32 v92, v92
	v_exp_f32_e32 v93, v93
	v_cvt_pk_bf16_f32 v188, v86, v87
	v_add_f32_e32 v86, v86, v87
	v_add_f32_e32 v217, v217, v84
	v_exp_f32_e32 v94, v94
	v_exp_f32_e32 v95, v95
	v_cvt_pk_bf16_f32 v189, v88, v89
	v_add_f32_e32 v88, v88, v89
	v_add_f32_e32 v217, v217, v86
	v_exp_f32_e32 v96, v96
	v_exp_f32_e32 v97, v97
	v_cvt_pk_bf16_f32 v190, v90, v91
	v_add_f32_e32 v90, v90, v91
	v_add_f32_e32 v217, v217, v88
	v_exp_f32_e32 v66, v66
	v_exp_f32_e32 v67, v67
	v_cvt_pk_bf16_f32 v191, v92, v93
	v_add_f32_e32 v92, v92, v93
	v_add_f32_e32 v217, v217, v90
	v_exp_f32_e32 v68, v68
	v_exp_f32_e32 v69, v69
	v_cvt_pk_bf16_f32 v192, v94, v95
	v_add_f32_e32 v94, v94, v95
	v_add_f32_e32 v217, v217, v92
	v_exp_f32_e32 v70, v70
	v_exp_f32_e32 v71, v71
	v_cvt_pk_bf16_f32 v193, v96, v97
	v_add_f32_e32 v96, v96, v97
	v_add_f32_e32 v217, v217, v94
	v_exp_f32_e32 v72, v72
	v_exp_f32_e32 v73, v73
	v_cvt_pk_bf16_f32 v218, v66, v67
	v_add_f32_e32 v66, v66, v67
	v_add_f32_e32 v217, v217, v96
	v_exp_f32_e32 v74, v74
	v_exp_f32_e32 v75, v75
	v_cvt_pk_bf16_f32 v219, v68, v69
	v_add_f32_e32 v68, v68, v69
	v_add_f32_e32 v216, v216, v66
	v_exp_f32_e32 v76, v76
	v_exp_f32_e32 v77, v77
	v_cvt_pk_bf16_f32 v220, v70, v71
	v_add_f32_e32 v70, v70, v71
	v_add_f32_e32 v216, v216, v68
	v_exp_f32_e32 v78, v78
	v_exp_f32_e32 v79, v79
	v_cvt_pk_bf16_f32 v221, v72, v73
	v_add_f32_e32 v72, v72, v73
	v_add_f32_e32 v216, v216, v70
	v_exp_f32_e32 v80, v80
	v_exp_f32_e32 v81, v81
	v_cvt_pk_bf16_f32 v222, v74, v75
	v_add_f32_e32 v74, v74, v75
	v_add_f32_e32 v216, v216, v72
	v_cvt_pk_bf16_f32 v223, v76, v77
	v_add_f32_e32 v76, v76, v77
	v_add_f32_e32 v216, v216, v74
	v_cvt_pk_bf16_f32 v224, v78, v79
	v_add_f32_e32 v78, v78, v79
	v_add_f32_e32 v216, v216, v76
	v_cvt_pk_bf16_f32 v225, v80, v81
	v_add_f32_e32 v80, v80, v81
	v_add_f32_e32 v216, v216, v78
	v_add_f32_e32 v216, v216, v80
	v_add_u32_e32 v235, s41, v32
	v_add_u32_e32 v234, s43, v245
	ds_read_b128 v[226:229], v235
	ds_read_b128 v[230:233], v235 offset:4608
	ds_read_b128 v[246:249], v235 offset:32
	s_waitcnt lgkmcnt(3)
	s_mov_b32 s6, s5
	s_mov_b32 s5, s41
	s_mov_b32 s41, s42
	s_mov_b32 s42, s6
	s_mov_b32 s4, s44
	s_cmp_eq_u32 s101, 0
	s_cbranch_scc0 .Lpp_nb_l2
	s_barrier
.Lpp_nb_l2:
	s_cmp_eq_u32 s44, 63
	s_cbranch_scc0 .LBB0_1013
	s_waitcnt lgkmcnt(2)
	v_mfma_f32_32x32x16_bf16 v[50:65], v[226:229], v[170:173], v[50:65]
	v_mfma_f32_32x32x16_bf16 v[16:31], v[226:229], v[174:177], v[16:31]
	ds_read_b128 v[226:229], v235 offset:4640
	s_waitcnt lgkmcnt(2)
	v_mfma_f32_32x32x16_bf16 v[34:49], v[230:233], v[170:173], v[34:49]
	v_mfma_f32_32x32x16_bf16 v[0:15], v[230:233], v[174:177], v[0:15]
	ds_read_b128 v[230:233], v235 offset:64
	s_waitcnt lgkmcnt(2)
	v_mfma_f32_32x32x16_bf16 v[50:65], v[246:249], v[166:169], v[50:65]
	v_mfma_f32_32x32x16_bf16 v[16:31], v[246:249], v[162:165], v[16:31]
	ds_read_b128 v[246:249], v235 offset:4672
	s_waitcnt lgkmcnt(2)
	v_mfma_f32_32x32x16_bf16 v[34:49], v[226:229], v[166:169], v[34:49]
	v_mfma_f32_32x32x16_bf16 v[0:15], v[226:229], v[162:165], v[0:15]
	ds_read_b128 v[226:229], v235 offset:96
	s_waitcnt lgkmcnt(2)
	v_mfma_f32_32x32x16_bf16 v[50:65], v[230:233], v[186:189], v[50:65]
	v_mfma_f32_32x32x16_bf16 v[16:31], v[230:233], v[218:221], v[16:31]
	ds_read_b128 v[230:233], v235 offset:4704
	s_waitcnt lgkmcnt(2)
	v_mfma_f32_32x32x16_bf16 v[34:49], v[246:249], v[186:189], v[34:49]
	v_mfma_f32_32x32x16_bf16 v[0:15], v[246:249], v[218:221], v[0:15]
	ds_read_b128 v[246:249], v234
	s_waitcnt lgkmcnt(2)
	v_mfma_f32_32x32x16_bf16 v[50:65], v[226:229], v[190:193], v[50:65]
	v_mfma_f32_32x32x16_bf16 v[16:31], v[226:229], v[222:225], v[16:31]
	ds_read_b128 v[226:229], v234 offset:32
	s_waitcnt lgkmcnt(2)
	v_mfma_f32_32x32x16_bf16 v[34:49], v[230:233], v[190:193], v[34:49]
	v_mfma_f32_32x32x16_bf16 v[0:15], v[230:233], v[222:225], v[0:15]
	ds_read_b128 v[230:233], v234 offset:64
	s_waitcnt lgkmcnt(2)
	v_mfma_f32_32x32x16_bf16 v[114:129], v[246:249], v[130:133], 0
	v_mfma_f32_32x32x16_bf16 v[98:113], v[246:249], v[146:149], 0
	ds_read_b128 v[246:249], v234 offset:96
	s_waitcnt lgkmcnt(2)
	v_mfma_f32_32x32x16_bf16 v[114:129], v[226:229], v[134:137], v[114:129]
	v_mfma_f32_32x32x16_bf16 v[98:113], v[226:229], v[150:153], v[98:113]
	ds_read_b128 v[226:229], v234 offset:4608
	s_waitcnt lgkmcnt(2)
	v_mfma_f32_32x32x16_bf16 v[114:129], v[230:233], v[138:141], v[114:129]
	v_mfma_f32_32x32x16_bf16 v[98:113], v[230:233], v[154:157], v[98:113]
	ds_read_b128 v[230:233], v234 offset:4640
	s_waitcnt lgkmcnt(2)
	v_mfma_f32_32x32x16_bf16 v[114:129], v[246:249], v[142:145], v[114:129]
	v_mfma_f32_32x32x16_bf16 v[98:113], v[246:249], v[158:161], v[98:113]
	ds_read_b128 v[246:249], v234 offset:4672
	s_waitcnt lgkmcnt(2)
	v_mfma_f32_32x32x16_bf16 v[82:97], v[226:229], v[130:133], 0
	v_mfma_f32_32x32x16_bf16 v[66:81], v[226:229], v[146:149], 0
	ds_read_b128 v[226:229], v234 offset:4704
	s_waitcnt lgkmcnt(2)
	v_mfma_f32_32x32x16_bf16 v[82:97], v[230:233], v[134:137], v[82:97]
	v_mfma_f32_32x32x16_bf16 v[66:81], v[230:233], v[150:153], v[66:81]
	s_waitcnt lgkmcnt(1)
	v_mfma_f32_32x32x16_bf16 v[82:97], v[246:249], v[138:141], v[82:97]
	v_mfma_f32_32x32x16_bf16 v[66:81], v[246:249], v[154:157], v[66:81]
	s_waitcnt lgkmcnt(0)
	v_mfma_f32_32x32x16_bf16 v[82:97], v[226:229], v[142:145], v[82:97]
	v_mfma_f32_32x32x16_bf16 v[66:81], v[226:229], v[158:161], v[66:81]
	s_cmp_eq_u32 s101, 1
	s_cbranch_scc0 .Lpp_nb_p1
	s_barrier
